# S5: a^16 load hoisted to the sequence header (the scan no longer waits vmcnt(0) behind 32 weight/u loads); waves 2-7 issue their output-GEMM weight and next-u loads after the barrier that releases the
# speedup vs baseline: 1.1297x; 1.0050x over previous
.LBB0_496:
	s_add_i32 s44, s51, s84
	s_cmpk_gt_i32 s44, 0x1ff
	v_mbcnt_lo_u32_b32 v157, -1, 0
	v_mbcnt_hi_u32_b32 v157, -1, v157
	s_cselect_b64 s[6:7], -1, 0
	v_add_u32_e32 v186, s33, v157
	s_and_b32 s45, s51, 31
	v_and_b32_e32 v252, 63, v157
	v_lshlrev_b32_e32 v252, 3, v252
	v_lshl_or_b32 v252, s45, 9, v252
	global_load_dwordx2 v[252:253], v252, s[88:89]
	s_ashr_i32 s0, s44, 5
	s_cmpk_lt_i32 s44, 0x200
	v_readfirstlane_b32 s23, v186
	s_cselect_b32 s0, s0, -1
	s_ashr_i32 s22, s23, 6
	v_and_b32_e32 v182, 15, v157
	s_lshl_b32 s26, s45, 17
	v_lshl_or_b32 v32, s22, 4, v182
	s_add_u32 s26, s92, s26
	v_ashrrev_i32_e32 v33, 31, v32
	s_addc_u32 s27, s93, 0
	v_lshlrev_b64 v[32:33], 9, v[32:33]
	v_lshl_add_u64 v[32:33], s[26:27], 0, v[32:33]
	v_and_b32_e32 v184, 48, v157
	v_lshl_add_u64 v[32:33], v[32:33], 0, v[184:185]
	global_load_dwordx4 v[48:51], v[32:33], off
	global_load_dwordx4 v[52:55], v[32:33], off offset:64
	global_load_dwordx4 v[56:59], v[32:33], off offset:128
	global_load_dwordx4 v[60:63], v[32:33], off offset:192
	global_load_dwordx4 v[44:47], v[32:33], off offset:256
	global_load_dwordx4 v[40:43], v[32:33], off offset:320
	global_load_dwordx4 v[36:39], v[32:33], off offset:384
	s_nop 0
	global_load_dwordx4 v[32:35], v[32:33], off offset:448
	v_and_b32_e32 v64, 31, v157
	v_ashrrev_i32_e32 v65, 5, v186
	v_lshlrev_b32_e32 v66, 9, v65
	v_bitop3_b32 v65, v65, v64, 15 bitop3:0x6c
	v_lshlrev_b32_e32 v65, 4, v65
	v_add3_u32 v65, 0, v66, v65
	v_add_u32_e32 v189, 0x200, v186
	s_waitcnt vmcnt(15)
	ds_write_b128 v65, v[0:3]
	v_ashrrev_i32_e32 v65, 5, v189
	v_lshlrev_b32_e32 v66, 9, v65
	v_bitop3_b32 v65, v65, v64, 15 bitop3:0x6c
	v_lshlrev_b32_e32 v65, 4, v65
	v_add3_u32 v65, 0, v66, v65
	v_add_u32_e32 v190, 0x400, v186
	s_waitcnt vmcnt(14)
	ds_write_b128 v65, v[4:7]
	v_ashrrev_i32_e32 v65, 5, v190
	v_lshlrev_b32_e32 v66, 9, v65
	v_bitop3_b32 v65, v65, v64, 15 bitop3:0x6c
	v_lshlrev_b32_e32 v65, 4, v65
	v_add3_u32 v65, 0, v66, v65
	v_add_u32_e32 v191, 0x600, v186
	s_waitcnt vmcnt(13)
	ds_write_b128 v65, v[8:11]
	v_ashrrev_i32_e32 v65, 5, v191
	v_lshlrev_b32_e32 v66, 9, v65
	v_bitop3_b32 v65, v65, v64, 15 bitop3:0x6c
	v_lshlrev_b32_e32 v65, 4, v65
	v_add3_u32 v65, 0, v66, v65
	v_add_u32_e32 v192, 0x800, v186
	s_waitcnt vmcnt(12)
	ds_write_b128 v65, v[12:15]
	v_ashrrev_i32_e32 v65, 5, v192
	v_lshlrev_b32_e32 v66, 9, v65
	v_bitop3_b32 v65, v65, v64, 15 bitop3:0x6c
	v_lshlrev_b32_e32 v65, 4, v65
	v_add3_u32 v65, 0, v66, v65
	v_add_u32_e32 v193, 0xa00, v186
	s_waitcnt vmcnt(11)
	ds_write_b128 v65, v[16:19]
	v_ashrrev_i32_e32 v65, 5, v193
	v_lshlrev_b32_e32 v66, 9, v65
	v_bitop3_b32 v65, v65, v64, 15 bitop3:0x6c
	v_lshlrev_b32_e32 v65, 4, v65
	v_add3_u32 v65, 0, v66, v65
	v_add_u32_e32 v194, 0xc00, v186
	s_waitcnt vmcnt(10)
	ds_write_b128 v65, v[20:23]
	v_ashrrev_i32_e32 v65, 5, v194
	v_lshlrev_b32_e32 v66, 9, v65
	v_bitop3_b32 v65, v65, v64, 15 bitop3:0x6c
	v_lshlrev_b32_e32 v65, 4, v65
	v_add3_u32 v65, 0, v66, v65
	v_add_u32_e32 v195, 0xe00, v186
	s_waitcnt vmcnt(9)
	ds_write_b128 v65, v[24:27]
	v_ashrrev_i32_e32 v65, 5, v195
	v_bitop3_b32 v64, v65, v64, 15 bitop3:0x6c
	v_lshlrev_b32_e32 v66, 9, v65
	v_lshlrev_b32_e32 v64, 4, v64
	v_bfe_u32 v156, v157, 4, 2
	v_add3_u32 v64, 0, v66, v64
	s_waitcnt vmcnt(8)
	ds_write_b128 v64, v[28:31]
	v_lshlrev_b32_e32 v196, 9, v182
	v_bitop3_b32 v64, v156, v157, 15 bitop3:0x78
	v_add_u32_e32 v100, 0, v196
	v_lshlrev_b32_e32 v64, 4, v64
	v_add_u32_e32 v197, v100, v64
	s_waitcnt lgkmcnt(0)
	s_barrier
	ds_read_b128 v[216:219], v197
	v_bitop3_b32 v72, v156, v182, 4 bitop3:0x36
	v_lshlrev_b32_e32 v72, 4, v72
	v_add_u32_e32 v198, v100, v72
	v_bitop3_b32 v72, v156, v182, 8 bitop3:0x36
	v_lshlrev_b32_e32 v72, 4, v72
	v_add_u32_e32 v199, v100, v72
	v_bitop3_b32 v72, v156, v182, 12 bitop3:0x36
	v_lshlrev_b32_e32 v72, 4, v72
	v_add_u32_e32 v200, v100, v72
	v_bitop3_b32 v72, v156, v182, 16 bitop3:0x36
	v_lshlrev_b32_e32 v72, 4, v72
	v_add_u32_e32 v201, v100, v72
	v_bitop3_b32 v72, v156, v182, 20 bitop3:0x36
	v_lshlrev_b32_e32 v72, 4, v72
	v_add_u32_e32 v202, v100, v72
	v_bitop3_b32 v72, v156, v182, 24 bitop3:0x36
	v_lshlrev_b32_e32 v72, 4, v72
	v_add_u32_e32 v203, v100, v72
	v_bitop3_b32 v72, v156, v182, 28 bitop3:0x36
	v_lshlrev_b32_e32 v72, 4, v72
	v_add_u32_e32 v204, v100, v72
	s_waitcnt vmcnt(7)
	ds_read_b128 v[220:223], v198
	ds_read_b128 v[228:231], v199
	ds_read_b128 v[232:235], v200
	ds_read_b128 v[236:239], v201
	s_waitcnt lgkmcnt(4)
	v_mfma_f32_16x16x32_bf16 v[64:67], v[216:219], v[48:51], 0
	s_and_b32 s50, s23, 0xffffffc0
	s_add_i32 s26, s50, 0
	s_waitcnt vmcnt(6)
	ds_read_b128 v[240:243], v202
	s_waitcnt lgkmcnt(4)
	v_mfma_f32_16x16x32_bf16 v[64:67], v[220:223], v[52:55], v[64:67]
	s_waitcnt vmcnt(5)
	ds_read_b128 v[244:247], v203
	s_waitcnt lgkmcnt(4)
	v_mfma_f32_16x16x32_bf16 v[64:67], v[228:231], v[56:59], v[64:67]
	s_waitcnt vmcnt(4)
	ds_read_b128 v[248:251], v204
	s_waitcnt lgkmcnt(4)
	v_mfma_f32_16x16x32_bf16 v[64:67], v[232:235], v[60:63], v[64:67]
	s_waitcnt vmcnt(3)
	ds_read_b128 v[216:219], v197 offset:8192
	s_waitcnt lgkmcnt(4)
	v_mfma_f32_16x16x32_bf16 v[64:67], v[236:239], v[44:47], v[64:67]
	s_waitcnt vmcnt(2)
	ds_read_b128 v[220:223], v198 offset:8192
	s_waitcnt lgkmcnt(4)
	v_mfma_f32_16x16x32_bf16 v[64:67], v[240:243], v[40:43], v[64:67]
	s_waitcnt vmcnt(1)
	ds_read_b128 v[228:231], v199 offset:8192
	s_waitcnt lgkmcnt(4)
	v_mfma_f32_16x16x32_bf16 v[64:67], v[244:247], v[36:39], v[64:67]
	s_waitcnt vmcnt(0)
	ds_read_b128 v[232:235], v200 offset:8192
	s_waitcnt lgkmcnt(4)
	v_mfma_f32_16x16x32_bf16 v[158:161], v[248:251], v[32:35], v[64:67]
	s_add_i32 s52, s26, 0x10000
	s_mul_i32 s26, s45, 0x30000
	s_add_u32 s26, s5, s26
	ds_read_b128 v[236:239], v201 offset:8192
	s_waitcnt lgkmcnt(4)
	v_mfma_f32_16x16x32_bf16 v[64:67], v[216:219], v[48:51], 0
	s_addc_u32 s27, s24, 0
	s_cmp_lt_i32 s0, 0
	v_ashrrev_i32_e32 v187, 31, v186
	ds_read_b128 v[240:243], v202 offset:8192
	s_waitcnt lgkmcnt(4)
	v_mfma_f32_16x16x32_bf16 v[64:67], v[220:223], v[52:55], v[64:67]
	ds_read_b128 v[244:247], v203 offset:8192
	s_waitcnt lgkmcnt(4)
	v_mfma_f32_16x16x32_bf16 v[64:67], v[228:231], v[56:59], v[64:67]
	ds_read_b128 v[248:251], v204 offset:8192
	s_waitcnt lgkmcnt(4)
	v_mfma_f32_16x16x32_bf16 v[64:67], v[232:235], v[60:63], v[64:67]
	ds_read_b128 v[216:219], v197 offset:16384
	s_waitcnt lgkmcnt(4)
	v_mfma_f32_16x16x32_bf16 v[64:67], v[236:239], v[44:47], v[64:67]
	ds_read_b128 v[220:223], v198 offset:16384
	s_waitcnt lgkmcnt(4)
	v_mfma_f32_16x16x32_bf16 v[64:67], v[240:243], v[40:43], v[64:67]
	ds_read_b128 v[228:231], v199 offset:16384
	s_waitcnt lgkmcnt(4)
	v_mfma_f32_16x16x32_bf16 v[64:67], v[244:247], v[36:39], v[64:67]
	ds_read_b128 v[232:235], v200 offset:16384
	s_waitcnt lgkmcnt(4)
	v_mfma_f32_16x16x32_bf16 v[162:165], v[248:251], v[32:35], v[64:67]
	s_nop 5
	ds_read_b128 v[236:239], v201 offset:16384
	s_waitcnt lgkmcnt(4)
	v_mfma_f32_16x16x32_bf16 v[64:67], v[216:219], v[48:51], 0
	ds_read_b128 v[240:243], v202 offset:16384
	s_waitcnt lgkmcnt(4)
	v_mfma_f32_16x16x32_bf16 v[64:67], v[220:223], v[52:55], v[64:67]
	ds_read_b128 v[244:247], v203 offset:16384
	s_waitcnt lgkmcnt(4)
	v_mfma_f32_16x16x32_bf16 v[64:67], v[228:231], v[56:59], v[64:67]
	ds_read_b128 v[248:251], v204 offset:16384
	s_waitcnt lgkmcnt(4)
	v_mfma_f32_16x16x32_bf16 v[64:67], v[232:235], v[60:63], v[64:67]
	ds_read_b128 v[216:219], v197 offset:24576
	s_waitcnt lgkmcnt(4)
	v_mfma_f32_16x16x32_bf16 v[64:67], v[236:239], v[44:47], v[64:67]
	ds_read_b128 v[220:223], v198 offset:24576
	s_waitcnt lgkmcnt(4)
	v_mfma_f32_16x16x32_bf16 v[64:67], v[240:243], v[40:43], v[64:67]
	ds_read_b128 v[228:231], v199 offset:24576
	s_waitcnt lgkmcnt(4)
	v_mfma_f32_16x16x32_bf16 v[64:67], v[244:247], v[36:39], v[64:67]
	ds_read_b128 v[232:235], v200 offset:24576
	s_waitcnt lgkmcnt(4)
	v_mfma_f32_16x16x32_bf16 v[166:169], v[248:251], v[32:35], v[64:67]
	ds_read_b128 v[236:239], v201 offset:24576
	s_waitcnt lgkmcnt(4)
	v_mfma_f32_16x16x32_bf16 v[64:67], v[216:219], v[48:51], 0
	ds_read_b128 v[240:243], v202 offset:24576
	s_waitcnt lgkmcnt(4)
	v_mfma_f32_16x16x32_bf16 v[64:67], v[220:223], v[52:55], v[64:67]
	ds_read_b128 v[244:247], v203 offset:24576
	s_waitcnt lgkmcnt(4)
	v_mfma_f32_16x16x32_bf16 v[64:67], v[228:231], v[56:59], v[64:67]
	ds_read_b128 v[248:251], v204 offset:24576
	s_waitcnt lgkmcnt(4)
	v_mfma_f32_16x16x32_bf16 v[64:67], v[232:235], v[60:63], v[64:67]
	ds_read_b128 v[216:219], v197 offset:32768
	s_waitcnt lgkmcnt(4)
	v_mfma_f32_16x16x32_bf16 v[64:67], v[236:239], v[44:47], v[64:67]
	ds_read_b128 v[220:223], v198 offset:32768
	s_waitcnt lgkmcnt(4)
	v_mfma_f32_16x16x32_bf16 v[64:67], v[240:243], v[40:43], v[64:67]
	ds_read_b128 v[228:231], v199 offset:32768
	s_waitcnt lgkmcnt(4)
	v_mfma_f32_16x16x32_bf16 v[64:67], v[244:247], v[36:39], v[64:67]
	ds_read_b128 v[232:235], v200 offset:32768
	s_waitcnt lgkmcnt(4)
	v_mfma_f32_16x16x32_bf16 v[170:173], v[248:251], v[32:35], v[64:67]
	s_nop 5
	ds_read_b128 v[236:239], v201 offset:32768
	s_waitcnt lgkmcnt(4)
	v_mfma_f32_16x16x32_bf16 v[64:67], v[216:219], v[48:51], 0
	ds_read_b128 v[240:243], v202 offset:32768
	s_waitcnt lgkmcnt(4)
	v_mfma_f32_16x16x32_bf16 v[64:67], v[220:223], v[52:55], v[64:67]
	ds_read_b128 v[244:247], v203 offset:32768
	s_waitcnt lgkmcnt(4)
	v_mfma_f32_16x16x32_bf16 v[64:67], v[228:231], v[56:59], v[64:67]
	ds_read_b128 v[248:251], v204 offset:32768
	s_waitcnt lgkmcnt(4)
	v_mfma_f32_16x16x32_bf16 v[64:67], v[232:235], v[60:63], v[64:67]
	ds_read_b128 v[216:219], v197 offset:40960
	s_waitcnt lgkmcnt(4)
	v_mfma_f32_16x16x32_bf16 v[64:67], v[236:239], v[44:47], v[64:67]
	ds_read_b128 v[220:223], v198 offset:40960
	s_waitcnt lgkmcnt(4)
	v_mfma_f32_16x16x32_bf16 v[64:67], v[240:243], v[40:43], v[64:67]
	ds_read_b128 v[228:231], v199 offset:40960
	s_waitcnt lgkmcnt(4)
	v_mfma_f32_16x16x32_bf16 v[64:67], v[244:247], v[36:39], v[64:67]
	ds_read_b128 v[232:235], v200 offset:40960
	s_waitcnt lgkmcnt(4)
	v_mfma_f32_16x16x32_bf16 v[174:177], v[248:251], v[32:35], v[64:67]
	ds_read_b128 v[236:239], v201 offset:40960
	s_waitcnt lgkmcnt(4)
	v_mfma_f32_16x16x32_bf16 v[64:67], v[216:219], v[48:51], 0
	ds_read_b128 v[240:243], v202 offset:40960
	s_waitcnt lgkmcnt(4)
	v_mfma_f32_16x16x32_bf16 v[64:67], v[220:223], v[52:55], v[64:67]
	ds_read_b128 v[244:247], v203 offset:40960
	s_waitcnt lgkmcnt(4)
	v_mfma_f32_16x16x32_bf16 v[64:67], v[228:231], v[56:59], v[64:67]
	ds_read_b128 v[248:251], v204 offset:40960
	s_waitcnt lgkmcnt(4)
	v_mfma_f32_16x16x32_bf16 v[64:67], v[232:235], v[60:63], v[64:67]
	ds_read_b128 v[216:219], v197 offset:49152
	s_waitcnt lgkmcnt(4)
	v_mfma_f32_16x16x32_bf16 v[64:67], v[236:239], v[44:47], v[64:67]
	ds_read_b128 v[220:223], v197 offset:57344
	s_waitcnt lgkmcnt(4)
	v_mfma_f32_16x16x32_bf16 v[64:67], v[240:243], v[40:43], v[64:67]
	ds_read_b128 v[228:231], v198 offset:49152
	s_waitcnt lgkmcnt(4)
	v_mfma_f32_16x16x32_bf16 v[64:67], v[244:247], v[36:39], v[64:67]
	ds_read_b128 v[232:235], v198 offset:57344
	s_waitcnt lgkmcnt(4)
	v_mfma_f32_16x16x32_bf16 v[178:181], v[248:251], v[32:35], v[64:67]
	s_nop 5
	ds_read_b128 v[236:239], v199 offset:49152
	s_waitcnt lgkmcnt(4)
	v_mfma_f32_16x16x32_bf16 v[64:67], v[216:219], v[48:51], 0
	ds_read_b128 v[240:243], v199 offset:57344
	s_waitcnt lgkmcnt(4)
	v_mfma_f32_16x16x32_bf16 v[48:51], v[220:223], v[48:51], 0
	ds_read_b128 v[244:247], v200 offset:49152
	s_waitcnt lgkmcnt(4)
	v_mfma_f32_16x16x32_bf16 v[64:67], v[228:231], v[52:55], v[64:67]
	ds_read_b128 v[248:251], v200 offset:57344
	s_waitcnt lgkmcnt(4)
	v_mfma_f32_16x16x32_bf16 v[48:51], v[232:235], v[52:55], v[48:51]
	ds_read_b128 v[216:219], v201 offset:49152
	s_waitcnt lgkmcnt(4)
	v_mfma_f32_16x16x32_bf16 v[64:67], v[236:239], v[56:59], v[64:67]
	ds_read_b128 v[220:223], v201 offset:57344
	s_waitcnt lgkmcnt(4)
	v_mfma_f32_16x16x32_bf16 v[48:51], v[240:243], v[56:59], v[48:51]
	ds_read_b128 v[228:231], v202 offset:49152
	s_waitcnt lgkmcnt(4)
	v_mfma_f32_16x16x32_bf16 v[64:67], v[244:247], v[60:63], v[64:67]
	ds_read_b128 v[232:235], v202 offset:57344
	s_waitcnt lgkmcnt(4)
	v_mfma_f32_16x16x32_bf16 v[48:51], v[248:251], v[60:63], v[48:51]
	ds_read_b128 v[236:239], v203 offset:49152
	s_waitcnt lgkmcnt(4)
	v_mfma_f32_16x16x32_bf16 v[64:67], v[216:219], v[44:47], v[64:67]
	ds_read_b128 v[240:243], v203 offset:57344
	s_waitcnt lgkmcnt(4)
	v_mfma_f32_16x16x32_bf16 v[44:47], v[220:223], v[44:47], v[48:51]
	ds_read_b128 v[244:247], v204 offset:49152
	s_waitcnt lgkmcnt(4)
	v_mfma_f32_16x16x32_bf16 v[64:67], v[228:231], v[40:43], v[64:67]
	ds_read_b128 v[248:251], v204 offset:57344
	s_waitcnt lgkmcnt(4)
	v_mfma_f32_16x16x32_bf16 v[40:43], v[232:235], v[40:43], v[44:47]
	s_waitcnt lgkmcnt(3)
	v_mfma_f32_16x16x32_bf16 v[64:67], v[236:239], v[36:39], v[64:67]
	v_lshl_or_b32 v46, s22, 5, v182
	v_lshl_add_u64 v[44:45], s[26:27], 0, v[184:185]
	s_waitcnt lgkmcnt(2)
	v_mfma_f32_16x16x32_bf16 v[36:39], v[240:243], v[36:39], v[40:43]
	s_nop 2
	v_mad_i64_i32 v[40:41], s[26:27], v46, s42, v[44:45]
	v_or_b32_e32 v46, 16, v46
	v_mad_i64_i32 v[44:45], s[26:27], v46, s42, v[44:45]
	s_waitcnt lgkmcnt(1)
	v_mfma_f32_16x16x32_bf16 v[210:213], v[244:247], v[32:35], v[64:67]
	s_cmp_gt_u32 s23, 0x7f
	s_cbranch_scc1 .Ls5_yb_late
	global_load_dwordx4 v[136:139], v[40:41], off
	global_load_dwordx4 v[120:123], v[40:41], off offset:64
	global_load_dwordx4 v[108:111], v[40:41], off offset:128
	global_load_dwordx4 v[100:103], v[40:41], off offset:192
	global_load_dwordx4 v[92:95], v[40:41], off offset:256
	global_load_dwordx4 v[84:87], v[40:41], off offset:320
	global_load_dwordx4 v[80:83], v[40:41], off offset:384
	global_load_dwordx4 v[76:79], v[40:41], off offset:448
	global_load_dwordx4 v[72:75], v[40:41], off offset:512
	global_load_dwordx4 v[68:71], v[40:41], off offset:576
	global_load_dwordx4 v[64:67], v[40:41], off offset:640
	s_nop 0
	global_load_dwordx4 v[40:43], v[40:41], off offset:704
	s_nop 0
	global_load_dwordx4 v[152:155], v[44:45], off
	global_load_dwordx4 v[148:151], v[44:45], off offset:64
	global_load_dwordx4 v[144:147], v[44:45], off offset:128
	global_load_dwordx4 v[140:143], v[44:45], off offset:192
	global_load_dwordx4 v[132:135], v[44:45], off offset:256
	global_load_dwordx4 v[128:131], v[44:45], off offset:320
	global_load_dwordx4 v[124:127], v[44:45], off offset:384
	global_load_dwordx4 v[116:119], v[44:45], off offset:448
	global_load_dwordx4 v[112:115], v[44:45], off offset:512
	global_load_dwordx4 v[104:107], v[44:45], off offset:576
	global_load_dwordx4 v[96:99], v[44:45], off offset:640
	global_load_dwordx4 v[88:91], v[44:45], off offset:704
.Ls5_yb_late:
	s_waitcnt lgkmcnt(0)
	v_mfma_f32_16x16x32_bf16 v[32:35], v[248:251], v[32:35], v[36:39]
	s_nop 2
	v_lshlrev_b32_e32 v36, 11, v156
	v_lshlrev_b32_e32 v37, 2, v182
	v_add3_u32 v36, s52, v37, v36
	ds_write2st64_b32 v36, v158, v159 offset1:2
	ds_write2st64_b32 v36, v160, v161 offset0:4 offset1:6
	ds_write2st64_b32 v36, v162, v163 offset0:32 offset1:34
	ds_write2st64_b32 v36, v164, v165 offset0:36 offset1:38
	ds_write2st64_b32 v36, v166, v167 offset0:64 offset1:66
	ds_write2st64_b32 v36, v168, v169 offset0:68 offset1:70
	ds_write2st64_b32 v36, v170, v171 offset0:96 offset1:98
	ds_write2st64_b32 v36, v172, v173 offset0:100 offset1:102
	ds_write2st64_b32 v36, v174, v175 offset0:128 offset1:130
	ds_write2st64_b32 v36, v176, v177 offset0:132 offset1:134
	ds_write2st64_b32 v36, v178, v179 offset0:160 offset1:162
	ds_write2st64_b32 v36, v180, v181 offset0:164 offset1:166
	ds_write2st64_b32 v36, v210, v211 offset0:192 offset1:194
	ds_write2st64_b32 v36, v212, v213 offset0:196 offset1:198
	ds_write2st64_b32 v36, v32, v33 offset0:224 offset1:226
	ds_write2st64_b32 v36, v34, v35 offset0:228 offset1:230
	s_cmp_gt_u32 s23, 0x7f
	s_cbranch_scc1 .LBB0_498
	s_cmp_lt_i32 s0, 0
	s_cbranch_scc1 .LBB0_498
	s_lshl_b64 s[26:27], s[0:1], 16
	s_add_u32 s0, s14, s26
	s_addc_u32 s27, s15, s27
	s_lshl_b32 s26, s44, 20
	s_and_b32 s26, s26, 0x1f00000
	s_add_u32 s26, s0, s26
	s_addc_u32 s27, s27, 0
	v_lshl_add_u64 v[24:25], v[186:187], 4, s[26:27]
	v_add_co_u32_e32 v4, vcc, s25, v24
	s_nop 1
	v_addc_co_u32_e32 v5, vcc, 0, v25, vcc
	v_add_co_u32_e32 v8, vcc, s36, v24
	global_load_dwordx4 v[0:3], v[24:25], off nt
	s_nop 0
	global_load_dwordx4 v[4:7], v[4:5], off nt
	v_addc_co_u32_e32 v9, vcc, 0, v25, vcc
	v_add_co_u32_e32 v12, vcc, s37, v24
	s_nop 1
	v_addc_co_u32_e32 v13, vcc, 0, v25, vcc
	v_add_co_u32_e32 v16, vcc, s38, v24
	global_load_dwordx4 v[8:11], v[8:9], off nt
	s_nop 0
	global_load_dwordx4 v[12:15], v[12:13], off nt
	v_addc_co_u32_e32 v17, vcc, 0, v25, vcc
	v_add_co_u32_e32 v20, vcc, s39, v24
	s_nop 1
	v_addc_co_u32_e32 v21, vcc, 0, v25, vcc
	v_add_co_u32_e32 v26, vcc, s40, v24
	global_load_dwordx4 v[16:19], v[16:17], off nt
	s_nop 0
	global_load_dwordx4 v[20:23], v[20:21], off nt
	v_addc_co_u32_e32 v27, vcc, 0, v25, vcc
	v_add_co_u32_e32 v28, vcc, s41, v24
	s_nop 1
	v_addc_co_u32_e32 v29, vcc, 0, v25, vcc
	global_load_dwordx4 v[24:27], v[26:27], off nt
	s_nop 0
	global_load_dwordx4 v[28:31], v[28:29], off nt
.LBB0_498:
	v_and_b32_e32 v38, 63, v157
	s_cmp_gt_u32 s23, 63
	s_waitcnt lgkmcnt(0)
	s_barrier
	s_cbranch_scc1 .LBB0_501
	v_mov_b32_e32 v32, v252
	v_mov_b32_e32 v36, 0
	v_lshlrev_b32_e32 v39, 1, v38
	v_lshlrev_b32_e32 v44, 2, v38
	s_mov_b32 s0, -16
	s_mov_b32 s23, 0
	v_mov_b32_e32 v37, v36
	v_mov_b32_e32 v33, v253
	v_pk_mov_b32 v[34:35], v[32:33], v[32:33] op_sel:[1,0]

.Ls5_late_loads:
	s_cmp_eq_u32 s22, 0
	s_cbranch_scc1 .LBB0_495
	global_load_dwordx4 v[136:139], v[40:41], off
	global_load_dwordx4 v[120:123], v[40:41], off offset:64
	global_load_dwordx4 v[108:111], v[40:41], off offset:128
	global_load_dwordx4 v[100:103], v[40:41], off offset:192
	global_load_dwordx4 v[92:95], v[40:41], off offset:256
	global_load_dwordx4 v[84:87], v[40:41], off offset:320
	global_load_dwordx4 v[80:83], v[40:41], off offset:384
	global_load_dwordx4 v[76:79], v[40:41], off offset:448
	global_load_dwordx4 v[72:75], v[40:41], off offset:512
	global_load_dwordx4 v[68:71], v[40:41], off offset:576
	global_load_dwordx4 v[64:67], v[40:41], off offset:640
	s_nop 0
	global_load_dwordx4 v[40:43], v[40:41], off offset:704
	s_nop 0
	global_load_dwordx4 v[152:155], v[44:45], off
	global_load_dwordx4 v[148:151], v[44:45], off offset:64
	global_load_dwordx4 v[144:147], v[44:45], off offset:128
	global_load_dwordx4 v[140:143], v[44:45], off offset:192
	global_load_dwordx4 v[132:135], v[44:45], off offset:256
	global_load_dwordx4 v[128:131], v[44:45], off offset:320
	global_load_dwordx4 v[124:127], v[44:45], off offset:384
	global_load_dwordx4 v[116:119], v[44:45], off offset:448
	global_load_dwordx4 v[112:115], v[44:45], off offset:512
	global_load_dwordx4 v[104:107], v[44:45], off offset:576
	global_load_dwordx4 v[96:99], v[44:45], off offset:640
	global_load_dwordx4 v[88:91], v[44:45], off offset:704
	s_cmp_lt_i32 s0, 0
	s_cbranch_scc1 .LBB0_495
	s_lshl_b64 s[26:27], s[0:1], 16
	s_add_u32 s0, s14, s26
	s_addc_u32 s27, s15, s27
	s_lshl_b32 s26, s44, 20
	s_and_b32 s26, s26, 0x1f00000
	s_add_u32 s26, s0, s26
	s_addc_u32 s27, s27, 0
	v_lshl_add_u64 v[24:25], v[186:187], 4, s[26:27]
	v_add_co_u32_e32 v4, vcc, s25, v24
	s_nop 1
	v_addc_co_u32_e32 v5, vcc, 0, v25, vcc
	v_add_co_u32_e32 v8, vcc, s36, v24
	global_load_dwordx4 v[0:3], v[24:25], off nt
	s_nop 0
	global_load_dwordx4 v[4:7], v[4:5], off nt
	v_addc_co_u32_e32 v9, vcc, 0, v25, vcc
	v_add_co_u32_e32 v12, vcc, s37, v24
	s_nop 1
	v_addc_co_u32_e32 v13, vcc, 0, v25, vcc
	v_add_co_u32_e32 v16, vcc, s38, v24
	global_load_dwordx4 v[8:11], v[8:9], off nt
	s_nop 0
	global_load_dwordx4 v[12:15], v[12:13], off nt
	v_addc_co_u32_e32 v17, vcc, 0, v25, vcc
	v_add_co_u32_e32 v20, vcc, s39, v24
	s_nop 1
	v_addc_co_u32_e32 v21, vcc, 0, v25, vcc
	v_add_co_u32_e32 v26, vcc, s40, v24
	global_load_dwordx4 v[16:19], v[16:17], off nt
	s_nop 0
	global_load_dwordx4 v[20:23], v[20:21], off nt
	v_addc_co_u32_e32 v27, vcc, 0, v25, vcc
	v_add_co_u32_e32 v28, vcc, s41, v24
	s_nop 1
	v_addc_co_u32_e32 v29, vcc, 0, v25, vcc
	global_load_dwordx4 v[24:27], v[26:27], off nt
	s_nop 0
	global_load_dwordx4 v[28:31], v[28:29], off nt
	s_branch .LBB0_495
